# attention inner loop hand-scheduled: K/V LDS reads prefetched 2 steps, softmax VALU interleaved in MFMA gaps, packed f32 ops split to scalar, SGPR-based tile addresses; same math
# speedup vs baseline: 1.0147x; 1.0147x over previous
; #define SBAR() __builtin_amdgcn_sched_barrier(0)
; #define SLOAD(i, k0) do { sr_[i].a0 = *reinterpret_cast<const bf16x8*>(&KVh[(size_t)((k0) + sr) * NKV + c16 * 8]); sr_[i].a1 = *reinterpret_cast<const bf16x8*>(&KVh[(size_t)((k0) + 32 + sr) * NKV + c16 * 8]); \
;     sr_[i].rr = *reinterpret_cast<const bf16x8*>(&KR[(size_t)((k0) + rkey) * 32 + rch * 8]); } while (0)
; #define SWRITE(b, i) do { if (isK) { *(bf16x8*)(K_lds + (b) * SHM_K + kst0) = sr_[i].a0; *(bf16x8*)(K_lds + (b) * SHM_K + kst1) = sr_[i].a1; } \
;     else { *(bf16x8*)(V_lds + (b) * SHM_V + vst0) = sr_[i].a0; *(bf16x8*)(V_lds + (b) * SHM_V + vst1) = sr_[i].a1; } \
;     if (rwr) *(bf16x8*)(K_lds + (b) * SHM_K + rst) = sr_[i].rr; } while (0)
; #define SWAIT() asm volatile("s_waitcnt vmcnt(3)" ::: "memory")
; __device__ __forceinline__ void attn_body(const bf16_t* __restrict__ Qb, const bf16_t* __restrict__ KVh, const bf16_t* __restrict__ KR, const float* __restrict__ ropeq,
;                                           bf16_t* __restrict__ Ob, int seq, char* lds, const int tid) {
;     ...
;     f32x16 pA0, pA1, pB0, pB1; float mnA, mnB, alA, alB; bf16x8 pa0, pa1, pa2, pa3; const int NT = seq / KVBLK;
;     constexpr int SE = 0, SO = 1;
;     SLOAD(SE, 0); asm volatile("s_waitcnt vmcnt(0)" ::: "memory"); SWRITE(0, SE); __syncthreads();
;     qkt(pA0, pA1, K_lds, qr, r32, hi); partialSM(pA0, pA1, m_reg, mnA, alA);
;     SLOAD(SO, KVBLK); if (2 < NT) SLOAD(SE, 2 * KVBLK);
;     SWAIT(); SWRITE(1, SO); __syncthreads();
;     int bp = 0, bc = 1, bn = 2;
;     for (int j = 1; j + 1 < NT; j += 2) {
;         SBAR(); qkt(pB0, pB1, K_lds + bc * SHM_K, qr, r32, hi);
;         finishSM(pA0, pA1, alA, l_reg, pa0, pa1, pa2, pa3); SBAR();
;         SLOAD(SO, (j + 2) * KVBLK); SBAR();
;         pv_d0(o, vb0 + bp * (int)SHM_V, pa0, pa1, pa2, pa3); partialSM(pB0, pB1, m_reg, mnB, alB);
;         SWAIT(); SWRITE(bn, SE);
.LBB0_51:
	s_or_b64 exec, exec, s[14:15]
	s_waitcnt vmcnt(3)
	v_max_f32_e32 v33, 0xf149f2ca, v44
	v_mov_b32_e32 v32, 0xf149f2ca
	v_cndmask_b32_e32 v179, v33, v32, vcc
	v_mul_f32_e32 v32, 0xbe16c740, v179
	v_pk_fma_f32 v[16:17], v[16:17], s[52:53], v[32:33] op_sel_hi:[1,0,0]
	s_lshr_b32 s14, s20, 4
	v_exp_f32_e32 v116, v16
	v_sub_f32_e32 v16, 0xf149f2ca, v33
	v_mul_f32_e32 v16, 0x3e16c740, v16
	v_exp_f32_e32 v16, v16
	v_pk_fma_f32 v[18:19], v[18:19], s[52:53], v[32:33] op_sel_hi:[1,0,0]
	v_pk_fma_f32 v[20:21], v[20:21], s[52:53], v[32:33] op_sel_hi:[1,0,0]
	v_pk_fma_f32 v[22:23], v[22:23], s[52:53], v[32:33] op_sel_hi:[1,0,0]
	v_pk_fma_f32 v[24:25], v[24:25], s[52:53], v[32:33] op_sel_hi:[1,0,0]
	v_pk_fma_f32 v[26:27], v[26:27], s[52:53], v[32:33] op_sel_hi:[1,0,0]
	v_pk_fma_f32 v[28:29], v[28:29], s[52:53], v[32:33] op_sel_hi:[1,0,0]
	v_pk_fma_f32 v[30:31], v[30:31], s[52:53], v[32:33] op_sel_hi:[1,0,0]
	s_and_b32 s14, s14, 15
	v_exp_f32_e32 v117, v17
	v_exp_f32_e32 v114, v18
	v_exp_f32_e32 v115, v19
	v_exp_f32_e32 v112, v20
	v_exp_f32_e32 v113, v21
	v_exp_f32_e32 v110, v22
	v_exp_f32_e32 v111, v23
	v_exp_f32_e32 v108, v24
	v_exp_f32_e32 v109, v25
	v_exp_f32_e32 v106, v26
	v_exp_f32_e32 v107, v27
	v_exp_f32_e32 v102, v28
	v_exp_f32_e32 v103, v29
	v_exp_f32_e32 v104, v30
	v_exp_f32_e32 v105, v31
	s_lshl_b32 s14, s14, 8
	v_pk_fma_f32 v[118:119], v[14:15], s[52:53], v[32:33] op_sel_hi:[1,0,0]
	s_add_u32 s6, s14, s6
	v_mov_b32_e32 v14, v65
	v_mov_b32_e32 v15, v65
	v_cndmask_b32_e64 v225, v16, 1.0, vcc
	v_pk_fma_f32 v[120:121], v[12:13], s[52:53], v[32:33] op_sel_hi:[1,0,0]
	v_pk_fma_f32 v[122:123], v[10:11], s[52:53], v[32:33] op_sel_hi:[1,0,0]
	v_pk_fma_f32 v[124:125], v[8:9], s[52:53], v[32:33] op_sel_hi:[1,0,0]
	v_pk_fma_f32 v[126:127], v[6:7], s[52:53], v[32:33] op_sel_hi:[1,0,0]
	v_pk_fma_f32 v[128:129], v[4:5], s[52:53], v[32:33] op_sel_hi:[1,0,0]
	v_pk_fma_f32 v[176:177], v[2:3], s[52:53], v[32:33] op_sel_hi:[1,0,0]
	v_pk_fma_f32 v[180:181], v[0:1], s[52:53], v[32:33] op_sel_hi:[1,0,0]
	s_addc_u32 s7, 0, s7
	v_mov_b32_e32 v0, v65
	v_mov_b32_e32 v1, v65
	v_mov_b32_e32 v2, v65
	v_mov_b32_e32 v3, v65
	v_mov_b32_e32 v4, v65
	v_mov_b32_e32 v5, v65
	v_mov_b32_e32 v6, v65
	v_mov_b32_e32 v7, v65
	v_mov_b32_e32 v8, v65
	v_mov_b32_e32 v9, v65
	v_mov_b32_e32 v10, v65
	v_mov_b32_e32 v11, v65
	v_mov_b32_e32 v12, v65
	v_mov_b32_e32 v13, v65
	v_mov_b64_e32 v[30:31], v[14:15]
	v_lshl_add_u64 v[168:169], s[6:7], 0, v[156:157]
	v_lshl_add_u64 v[170:171], v[158:159], 0, s[12:13]
	v_lshl_add_u64 v[172:173], v[160:161], 0, s[12:13]
	s_mov_b32 s16, 0
	v_mov_b32_e32 v163, 0
	s_mov_b32 s6, 2
	s_mov_b32 s17, 1
	v_mov_b64_e32 v[28:29], v[12:13]
	v_mov_b64_e32 v[26:27], v[10:11]
	v_mov_b64_e32 v[24:25], v[8:9]
	v_mov_b64_e32 v[22:23], v[6:7]
	v_mov_b64_e32 v[20:21], v[4:5]
	v_mov_b64_e32 v[18:19], v[2:3]
	v_mov_b64_e32 v[16:17], v[0:1]
	s_mov_b32 s18, 1
	s_load_dwordx2 s[26:27], s[94:95], 0xb8
	s_mov_b32 s24, 0x2000
	s_mov_b32 s25, 0
	s_waitcnt lgkmcnt(0)
	s_add_u32 s28, s26, 0x10cc0000
	s_addc_u32 s29, s27, 0
	s_add_u32 s30, s26, 0x10ce0000
	s_addc_u32 s31, s27, 0
	s_add_u32 s40, s26, 0x10d00000
	s_addc_u32 s41, s27, 0
	s_add_u32 s42, s26, 0x10d20000
	s_addc_u32 s43, s27, 0
	s_waitcnt lgkmcnt(0)
	s_barrier
.Lattn_loop:
	s_mov_b32 s19, s6
	s_lshl_b32 s14, s18, 14
	s_lshl_b32 s22, s16, 14
	s_lshl_b32 s15, s19, 14
	v_add_u32_e32 v254, s14, v188
	ds_read_b128 v[234:237], v254 offset:49152
	ds_read_b128 v[238:241], v254 offset:57344
	v_add_u32_e32 v254, s14, v189
	ds_read_b128 v[242:245], v254 offset:49152
	ds_read_b128 v[246:249], v254 offset:57344
	v_exp_f32_e32 v226, v124
	v_exp_f32_e32 v227, v125
	v_add_f32_e32 v250, v116, v114
	v_add_f32_e32 v251, v117, v115
	v_add_f32_e32 v250, v112, v250
	v_add_f32_e32 v251, v113, v251
	v_exp_f32_e32 v228, v122
	v_exp_f32_e32 v229, v123
	s_waitcnt lgkmcnt(3)
	v_mfma_f32_32x32x16_bf16 v[48:63], v[234:237], v[78:81], 0
	v_add_f32_e32 v250, v110, v250
	v_add_f32_e32 v251, v111, v251
	v_add_f32_e32 v250, v108, v250
	v_add_f32_e32 v251, v109, v251
	v_exp_f32_e32 v230, v120
	v_exp_f32_e32 v231, v121
	v_add_f32_e32 v250, v106, v250
	v_add_f32_e32 v251, v107, v251
	s_waitcnt lgkmcnt(2)
	v_mfma_f32_32x32x16_bf16 v[32:47], v[238:241], v[78:81], 0
	v_add_u32_e32 v254, s14, v212
	ds_read_b128 v[234:237], v254 offset:49152
	ds_read_b128 v[238:241], v254 offset:57344
	v_add_f32_e32 v250, v102, v250
	v_add_f32_e32 v251, v103, v251
	v_exp_f32_e32 v232, v118
	v_exp_f32_e32 v233, v119
	v_add_f32_e32 v250, v104, v250
	v_add_f32_e32 v251, v105, v251
	v_cvt_pk_bf16_f32 v116, v116, v117
	s_waitcnt lgkmcnt(3)
	v_mfma_f32_32x32x16_bf16 v[48:63], v[242:245], v[74:77], v[48:63]
	v_cvt_pk_bf16_f32 v117, v114, v115
	v_cvt_pk_bf16_f32 v118, v112, v113
	v_cvt_pk_bf16_f32 v119, v110, v111
	s_nop 0
	v_permlane32_swap_b32_e32 v116, v118
	v_permlane32_swap_b32_e32 v117, v119
	s_waitcnt lgkmcnt(2)
	v_mfma_f32_32x32x16_bf16 v[32:47], v[246:249], v[74:77], v[32:47]
	v_add_u32_e32 v254, s14, v213
	ds_read_b128 v[242:245], v254 offset:49152
	ds_read_b128 v[246:249], v254 offset:57344
	v_cvt_pk_bf16_f32 v120, v108, v109
	v_cvt_pk_bf16_f32 v121, v106, v107
	v_cvt_pk_bf16_f32 v122, v102, v103
	v_cvt_pk_bf16_f32 v123, v104, v105
	s_nop 0
	v_permlane32_swap_b32_e32 v120, v122
	s_waitcnt lgkmcnt(3)
	v_mfma_f32_32x32x16_bf16 v[48:63], v[234:237], v[70:73], v[48:63]
	v_permlane32_swap_b32_e32 v121, v123
	v_exp_f32_e32 v180, v180
	v_exp_f32_e32 v181, v181
	v_exp_f32_e32 v176, v176
	v_exp_f32_e32 v177, v177
	s_waitcnt vmcnt(0)
	v_add_u32_e32 v254, s15, v217
	v_add_u32_e32 v255, v254, v218
	v_add_u32_e32 v254, v254, v219
	ds_write_b128 v255, v[90:93]
	ds_write_b128 v254, v[94:97]
	s_cmp_eq_u64 s[2:3], 0
	s_cbranch_scc1 .Lattn_swB
	v_add_u32_e32 v254, s15, v186
	ds_write_b128 v254, v[98:101] offset:49152
; #define SBAR() __builtin_amdgcn_sched_barrier(0)
; __device__ __forceinline__ void partialSM(f32x16& p0, f32x16& p1, float& m_reg, float& mn, float& alpha) {
;     constexpr float Cc = SCALE * 1.4426950408889634f;
;     float pmax = p0[0];
; #pragma unroll
;     for (int r = 1; r < 16; ++r) pmax = fmaxf(pmax, p0[r]);
; #pragma unroll
;     for (int r = 0; r < 16; ++r) pmax = fmaxf(pmax, p1[r]);
; __device__ __forceinline__ void qkt(f32x16& p0, f32x16& p1, const char* Ks, const bf16x8* qr, int r32, int hi) {
;     p0 = f32x16{}; p1 = f32x16{};
; #pragma unroll
;     for (int d0 = 0; d0 < 6; ++d0) { const int cb = (d0 * 16 + hi * 8) * 2;
;         bf16x8 b0 = *reinterpret_cast<const bf16x8*>(Ks + KSWZ(r32, cb));
;         bf16x8 b1 = *reinterpret_cast<const bf16x8*>(Ks + KSWZ(32 + r32, cb));
;         p0 = __builtin_amdgcn_mfma_f32_32x32x16_bf16(b0, qr[d0], p0, 0, 0, 0);
;         p1 = __builtin_amdgcn_mfma_f32_32x32x16_bf16(b1, qr[d0], p1, 0, 0, 0); }
; }
; __device__ __forceinline__ int v_st(int k, int c) { const int kk = (k & ~0xC) | ((k & 4) << 1) | ((k & 8) >> 1); return ((kk >> 3) * 4 + (c >> 5)) * 512 + ((kk & 7) * 32 + (c & 31)) * 2; }
; __device__ __forceinline__ int v_rd_base(int lane) { return ((lane & 3) << 3) | (((lane >> 2) & 3) << 6) | (((lane >> 4) & 1) << 5) | (((lane >> 5) & 1) << 8); }
; template <int OFF> __device__ __forceinline__ s16x4 tr_read(int vb) {
;     s16x4 r; asm volatile("ds_read_b64_tr_b16 %0, %1 offset:%2" : "=&v"(r) : "v"(vb), "i"(OFF) : "memory"); return r;
; }
; template <int D0> __device__ __forceinline__ void pv_one(f32x16& od, int vb, bf16x8 pa0, bf16x8 pa1, bf16x8 pa2, bf16x8 pa3) {
;     const s16x4 l0 = tr_read<v_rd_off(D0, 0, 0)>(vb), h0 = tr_read<v_rd_off(D0, 0, 1)>(vb), l1 = tr_read<v_rd_off(D0, 1, 0)>(vb), h1 = tr_read<v_rd_off(D0, 1, 1)>(vb);
;     const s16x4 l2 = tr_read<v_rd_off(D0, 2, 0)>(vb), h2 = tr_read<v_rd_off(D0, 2, 1)>(vb), l3 = tr_read<v_rd_off(D0, 3, 0)>(vb), h3 = tr_read<v_rd_off(D0, 3, 1)>(vb);
;     asm volatile("s_waitcnt lgkmcnt(0)" ::: "memory"); SBAR();
;     ...
;     od = __builtin_amdgcn_mfma_f32_32x32x16_bf16(pa0, PK(l0, h0), od, 0, 0, 0);
;     od = __builtin_amdgcn_mfma_f32_32x32x16_bf16(pa1, PK(l1, h1), od, 0, 0, 0);
;     od = __builtin_amdgcn_mfma_f32_32x32x16_bf16(pa2, PK(l2, h2), od, 0, 0, 0);
;     od = __builtin_amdgcn_mfma_f32_32x32x16_bf16(pa3, PK(l3, h3), od, 0, 0, 0);
;     ...
; }
.Lattn_swB:
	s_waitcnt lgkmcnt(4)
	v_mfma_f32_32x32x16_bf16 v[32:47], v[238:241], v[70:73], v[32:47]
	v_add_u32_e32 v254, s14, v214
	ds_read_b128 v[234:237], v254 offset:49152
	ds_read_b128 v[238:241], v254 offset:57344
	v_exp_f32_e32 v128, v128
	v_exp_f32_e32 v129, v129
	v_exp_f32_e32 v202, v126
	v_exp_f32_e32 v203, v127
	s_waitcnt lgkmcnt(5)
	v_mfma_f32_32x32x16_bf16 v[48:63], v[242:245], v[66:69], v[48:63]
	v_add_f32_e32 v174, v180, v176
	v_add_f32_e32 v175, v181, v177
	v_add_f32_e32 v174, v128, v174
	v_add_f32_e32 v175, v129, v175
	v_add_f32_e32 v174, v202, v174
	v_add_f32_e32 v175, v203, v175
	v_add_f32_e32 v174, v226, v174
	v_add_f32_e32 v175, v227, v175
	v_lshl_add_u64 v[106:107], s[28:29], 0, v[168:169]
	global_load_dwordx4 v[106:109], v[106:107], off
	v_lshl_add_u64 v[110:111], s[30:31], 0, v[168:169]
	global_load_dwordx4 v[110:113], v[110:111], off
	v_lshl_add_u64 v[102:103], s[26:27], 0, v[172:173]
	global_load_dwordx4 v[102:105], v[102:103], off
	s_waitcnt lgkmcnt(4)
	v_mfma_f32_32x32x16_bf16 v[32:47], v[246:249], v[66:69], v[32:47]
	v_add_u32_e32 v254, s14, v215
	ds_read_b128 v[242:245], v254 offset:49152
	ds_read_b128 v[246:249], v254 offset:57344
	v_add_f32_e32 v174, v228, v174
	v_add_f32_e32 v175, v229, v175
	v_add_f32_e32 v174, v230, v174
	v_add_f32_e32 v175, v231, v175
	v_add_f32_e32 v174, v232, v174
	v_add_f32_e32 v175, v233, v175
	v_add_f32_e32 v250, v250, v174
	v_add_f32_e32 v251, v251, v175
	s_waitcnt lgkmcnt(3)
	v_mfma_f32_32x32x16_bf16 v[48:63], v[234:237], v[82:85], v[48:63]
	v_add_f32_e32 v174, v250, v251
	v_add_f32_e32 v175, v251, v250
	v_mov_b32_e32 v175, v174
	s_nop 1
	v_permlane32_swap_b32_e32 v174, v175
	v_cvt_pk_bf16_f32 v124, v180, v181
	s_waitcnt lgkmcnt(2)
	v_mfma_f32_32x32x16_bf16 v[32:47], v[238:241], v[82:85], v[32:47]
	v_add_u32_e32 v255, s22, v185
	ds_read_b64_tr_b16 v[234:235], v255 offset:0
	ds_read_b64_tr_b16 v[236:237], v255 offset:2048
	ds_read_b64_tr_b16 v[238:239], v255 offset:4096
	ds_read_b64_tr_b16 v[240:241], v255 offset:6144
	v_cvt_pk_bf16_f32 v125, v176, v177
	v_cvt_pk_bf16_f32 v126, v128, v129
	v_cvt_pk_bf16_f32 v127, v202, v203
	s_nop 0
	v_permlane32_swap_b32_e32 v124, v126
	s_waitcnt lgkmcnt(5)
	v_mfma_f32_32x32x16_bf16 v[48:63], v[242:245], v[86:89], v[48:63]
	v_permlane32_swap_b32_e32 v125, v127
	v_cvt_pk_bf16_f32 v226, v226, v227
	v_cvt_pk_bf16_f32 v227, v228, v229
	v_cvt_pk_bf16_f32 v228, v230, v231
	s_waitcnt lgkmcnt(4)
	v_mfma_f32_32x32x16_bf16 v[32:47], v[246:249], v[86:89], v[32:47]
	ds_read_b64_tr_b16 v[242:243], v255 offset:8192
	ds_read_b64_tr_b16 v[244:245], v255 offset:10240
	ds_read_b64_tr_b16 v[246:247], v255 offset:12288
	ds_read_b64_tr_b16 v[248:249], v255 offset:14336
	v_cvt_pk_bf16_f32 v229, v232, v233
	v_permlane32_swap_b32_e32 v226, v228
	s_nop 0
	v_permlane32_swap_b32_e32 v227, v229
	s_waitcnt lgkmcnt(6)
	v_mfma_f32_32x32x16_bf16 v[0:15], v[116:119], v[234:237], v[0:15]
	ds_read_b64_tr_b16 v[234:235], v255 offset:512
	ds_read_b64_tr_b16 v[236:237], v255 offset:2560
	v_max_f32_e32 v90, v48, v49
	v_max_f32_e32 v91, v32, v33
	v_max3_f32 v90, v90, v50, v51
	v_max3_f32 v91, v91, v34, v35
	v_max3_f32 v90, v90, v52, v53
	v_max3_f32 v91, v91, v36, v37
	s_waitcnt lgkmcnt(6)
	v_mfma_f32_32x32x16_bf16 v[0:15], v[120:123], v[238:241], v[0:15]
	ds_read_b64_tr_b16 v[238:239], v255 offset:4608
	ds_read_b64_tr_b16 v[240:241], v255 offset:6656
	v_max3_f32 v90, v90, v54, v55
	v_max3_f32 v91, v91, v38, v39
	v_max3_f32 v90, v90, v56, v57
	v_max3_f32 v91, v91, v40, v41
	v_max3_f32 v90, v90, v58, v59
	v_max3_f32 v91, v91, v42, v43
	v_max3_f32 v90, v90, v60, v61
	s_waitcnt lgkmcnt(6)
	v_mfma_f32_32x32x16_bf16 v[0:15], v[124:127], v[242:245], v[0:15]
	ds_read_b64_tr_b16 v[242:243], v255 offset:8704
	ds_read_b64_tr_b16 v[244:245], v255 offset:10752
	v_max3_f32 v91, v91, v44, v45
	v_max3_f32 v90, v90, v62, v63
	v_max3_f32 v91, v91, v46, v47
	v_max_f32_e32 v90, v90, v91
	v_mov_b32_e32 v91, v90
	s_nop 1
	v_permlane32_swap_b32_e32 v90, v91
	v_max_f32_e32 v90, v90, v91
	s_waitcnt lgkmcnt(6)
	v_mfma_f32_32x32x16_bf16 v[0:15], v[226:229], v[246:249], v[0:15]
	ds_read_b64_tr_b16 v[246:247], v255 offset:12800
	ds_read_b64_tr_b16 v[248:249], v255 offset:14848
	v_sub_f32_e32 v92, v90, v179
	v_cmp_ge_f32_e32 vcc, s67, v92
	v_max_f32_e32 v90, v179, v90
	v_sub_f32_e32 v92, v179, v90
	v_mul_f32_e32 v92, 0x3e16c740, v92
	v_exp_f32_e32 v93, v92
	s_cmp_eq_u64 vcc, exec
	s_waitcnt lgkmcnt(6)
	v_mfma_f32_32x32x16_bf16 v[16:31], v[116:119], v[234:237], v[16:31]
	s_cselect_b64 s[44:45], -1, 0
	v_cndmask_b32_e64 v180, v90, v179, s[44:45]
	v_mul_f32_e32 v94, 0xbe16c740, v180
	v_fma_f32 v48, v48, s52, v94
	v_fma_f32 v49, v49, s52, v94
	v_fma_f32 v50, v50, s52, v94
	v_fma_f32 v51, v51, s52, v94
	v_fma_f32 v52, v52, s52, v94
	v_fma_f32 v53, v53, s52, v94
	v_exp_f32_e32 v234, v50
	v_exp_f32_e32 v235, v51
	v_exp_f32_e32 v236, v52
	v_exp_f32_e32 v237, v53
	s_waitcnt lgkmcnt(4)
	v_mfma_f32_32x32x16_bf16 v[16:31], v[120:123], v[238:241], v[16:31]
	v_fma_f32 v54, v54, s52, v94
	v_fma_f32 v55, v55, s52, v94
	v_fma_f32 v56, v56, s52, v94
	v_fma_f32 v57, v57, s52, v94
	v_fma_f32 v58, v58, s52, v94
	v_fma_f32 v59, v59, s52, v94
	v_fma_f32 v60, v60, s52, v94
	v_fma_f32 v61, v61, s52, v94
	v_fma_f32 v62, v62, s52, v94
	v_fma_f32 v63, v63, s52, v94
	v_fma_f32 v128, v38, s52, v94
	v_fma_f32 v129, v39, s52, v94
	v_exp_f32_e32 v238, v54
	v_exp_f32_e32 v239, v55
	v_exp_f32_e32 v240, v56
	v_exp_f32_e32 v241, v57
	v_fma_f32 v122, v32, s52, v94
	v_fma_f32 v123, v33, s52, v94
	s_waitcnt lgkmcnt(2)
	v_mfma_f32_32x32x16_bf16 v[16:31], v[124:127], v[242:245], v[16:31]
	v_fma_f32 v178, v40, s52, v94
	v_fma_f32 v179, v41, s52, v94
	v_fma_f32 v202, v42, s52, v94
	v_fma_f32 v203, v43, s52, v94
	v_fma_f32 v230, v46, s52, v94
	v_fma_f32 v231, v47, s52, v94
	v_exp_f32_e32 v232, v48
	v_exp_f32_e32 v233, v49
	v_exp_f32_e32 v242, v58
	v_exp_f32_e32 v243, v59
	v_exp_f32_e32 v244, v60
	v_exp_f32_e32 v245, v61
	v_fma_f32 v124, v34, s52, v94
	v_fma_f32 v125, v35, s52, v94
	v_fma_f32 v126, v36, s52, v94
	v_fma_f32 v127, v37, s52, v94
	s_waitcnt lgkmcnt(0)
	v_mfma_f32_32x32x16_bf16 v[16:31], v[226:229], v[246:249], v[16:31]
	v_exp_f32_e32 v246, v62
	v_exp_f32_e32 v247, v63
	v_fma_f32 v228, v44, s52, v94
	v_fma_f32 v229, v45, s52, v94
	v_cndmask_b32_e64 v227, v93, 1.0, s[44:45]
	v_cmp_gt_f32_e32 vcc, 1.0, v227
	s_cbranch_vccz .Lattn_rsB
; #define SBAR() __builtin_amdgcn_sched_barrier(0)
; #define SLOAD(i, k0) do { sr_[i].a0 = *reinterpret_cast<const bf16x8*>(&KVh[(size_t)((k0) + sr) * NKV + c16 * 8]); sr_[i].a1 = *reinterpret_cast<const bf16x8*>(&KVh[(size_t)((k0) + 32 + sr) * NKV + c16 * 8]); \
;     sr_[i].rr = *reinterpret_cast<const bf16x8*>(&KR[(size_t)((k0) + rkey) * 32 + rch * 8]); } while (0)
; #define SWRITE(b, i) do { if (isK) { *(bf16x8*)(K_lds + (b) * SHM_K + kst0) = sr_[i].a0; *(bf16x8*)(K_lds + (b) * SHM_K + kst1) = sr_[i].a1; } \
;     else { *(bf16x8*)(V_lds + (b) * SHM_V + vst0) = sr_[i].a0; *(bf16x8*)(V_lds + (b) * SHM_V + vst1) = sr_[i].a1; } \
;     if (rwr) *(bf16x8*)(K_lds + (b) * SHM_K + rst) = sr_[i].rr; } while (0)
; #define SWAIT() asm volatile("s_waitcnt vmcnt(3)" ::: "memory")
; __device__ __forceinline__ void finishSM(f32x16& p0, f32x16& p1, float alpha, float& l_reg, bf16x8& pa0, bf16x8& pa1, bf16x8& pa2, bf16x8& pa3) {
; #pragma unroll
;     for (int r = 0; r < 16; ++r) p1[r] = __builtin_amdgcn_exp2f(p1[r]);
;     float ps;
;     { typedef float f32x2 __attribute__((ext_vector_type(2))); f32x2 s0 = {p0[0], p0[1]}, s1 = {p1[0], p1[1]};
; #pragma unroll
;       for (int r = 2; r < 16; r += 2) { s0 += (f32x2){p0[r], p0[r + 1]}; s1 += (f32x2){p1[r], p1[r + 1]}; }
;       s0 += s1; ps = s0.x + s0.y; }
;     { auto rr = __builtin_amdgcn_permlane32_swap(__float_as_uint(ps), __float_as_uint(ps), false, false);
;       ps = __uint_as_float(rr[0]) + __uint_as_float(rr[1]); }
;     l_reg = l_reg * alpha + ps;
;     ...
;     PK4(p0, 0, pa0); PK4(p0, 8, pa1); PK4(p1, 0, pa2); PK4(p1, 8, pa3);
; __device__ __forceinline__ void attn_body(const bf16_t* __restrict__ Qb, const bf16_t* __restrict__ KVh, const bf16_t* __restrict__ KR, const float* __restrict__ ropeq,
;                                           bf16_t* __restrict__ Ob, int seq, char* lds, const int tid) {
;     ...
;         RESC(alB); __syncthreads();
;         { const int t = bp; bp = bc; bc = bn; bn = t; }
;         SBAR(); qkt(pA0, pA1, K_lds + bc * SHM_K, qr, r32, hi);
;         finishSM(pB0, pB1, alB, l_reg, pa0, pa1, pa2, pa3); SBAR();
;         if (j + 3 < NT) SLOAD(SE, (j + 3) * KVBLK); SBAR();
;         pv_d0(o, vb0 + bp * (int)SHM_V, pa0, pa1, pa2, pa3); partialSM(pA0, pA1, m_reg, mnA, alA);
;         SWAIT(); SWRITE(bn, SO);
	s_nop 7
	s_nop 5
	s_and_saveexec_b64 s[46:47], s[4:5]
	ds_write_b32 v216, v227 offset:128
	s_or_b64 exec, exec, s[46:47]
	s_waitcnt lgkmcnt(0)
	v_add_u32_e32 v96, v139, v187
	ds_read_b128 v[116:119], v96 offset:192
	ds_read_b128 v[92:95], v96 offset:160
	ds_read_b128 v[248:251], v96 offset:128
	ds_read_b128 v[96:99], v96 offset:224
	s_waitcnt lgkmcnt(0)
	v_mul_f32_e32 v12, v12, v96
	v_mul_f32_e32 v13, v13, v97
	v_mul_f32_e32 v14, v14, v98
	v_mul_f32_e32 v15, v15, v99
	v_mul_f32_e32 v8, v8, v116
	v_mul_f32_e32 v9, v9, v117
	v_mul_f32_e32 v10, v10, v118
	v_mul_f32_e32 v11, v11, v119
	v_mul_f32_e32 v4, v4, v92
	v_mul_f32_e32 v5, v5, v93
	v_mul_f32_e32 v6, v6, v94
	v_mul_f32_e32 v7, v7, v95
	v_mul_f32_e32 v0, v0, v248
	v_mul_f32_e32 v1, v1, v249
	v_mul_f32_e32 v2, v2, v250
	v_mul_f32_e32 v3, v3, v251
	v_mul_f32_e32 v28, v28, v96
	v_mul_f32_e32 v29, v29, v97
	v_mul_f32_e32 v30, v30, v98
	v_mul_f32_e32 v31, v31, v99
	v_mul_f32_e32 v24, v24, v116
	v_mul_f32_e32 v25, v25, v117
	v_mul_f32_e32 v26, v26, v118
	v_mul_f32_e32 v27, v27, v119
	v_mul_f32_e32 v20, v20, v92
	v_mul_f32_e32 v21, v21, v93
	v_mul_f32_e32 v22, v22, v94
	v_mul_f32_e32 v23, v23, v95
	v_mul_f32_e32 v16, v16, v248
	v_mul_f32_e32 v17, v17, v249
	v_mul_f32_e32 v18, v18, v250
	v_mul_f32_e32 v19, v19, v251
.Lattn_rsB:
	s_waitcnt lgkmcnt(0)
	s_barrier
	v_add_u32_e32 v254, s15, v188
	ds_read_b128 v[114:117], v254 offset:49152
	ds_read_b128 v[118:121], v254 offset:57344
	v_add_f32_e32 v176, v232, v234
	v_add_f32_e32 v177, v233, v235
	v_cvt_pk_bf16_f32 v232, v232, v233
	v_cvt_pk_bf16_f32 v233, v234, v235
	v_add_f32_e32 v176, v236, v176
	v_add_f32_e32 v177, v237, v177
	v_cvt_pk_bf16_f32 v234, v236, v237
	v_add_f32_e32 v176, v238, v176
	v_add_f32_e32 v177, v239, v177
	v_cvt_pk_bf16_f32 v235, v238, v239
	v_add_f32_e32 v176, v240, v176
	v_add_f32_e32 v177, v241, v177
	v_cvt_pk_bf16_f32 v236, v240, v241
	v_add_f32_e32 v176, v242, v176
	v_add_f32_e32 v177, v243, v177
	v_cvt_pk_bf16_f32 v237, v242, v243
	v_add_u32_e32 v254, s15, v189
	ds_read_b128 v[248:251], v254 offset:49152
	ds_read_b128 v[240:243], v254 offset:57344
	v_add_f32_e32 v176, v244, v176
	v_add_f32_e32 v177, v245, v177
	v_cvt_pk_bf16_f32 v238, v244, v245
	s_waitcnt lgkmcnt(3)
	v_mfma_f32_32x32x16_bf16 v[48:63], v[114:117], v[78:81], 0
	v_add_f32_e32 v176, v246, v176
	v_add_f32_e32 v177, v247, v177
	v_cvt_pk_bf16_f32 v239, v246, v247
	v_permlane32_swap_b32_e32 v232, v234
	v_permlane32_swap_b32_e32 v233, v235
	s_waitcnt lgkmcnt(2)
	v_mfma_f32_32x32x16_bf16 v[32:47], v[118:121], v[78:81], 0
	v_add_u32_e32 v254, s15, v212
	ds_read_b128 v[114:117], v254 offset:49152
	ds_read_b128 v[118:121], v254 offset:57344
	v_permlane32_swap_b32_e32 v236, v238
	v_permlane32_swap_b32_e32 v237, v239
	v_exp_f32_e32 v122, v122
	v_exp_f32_e32 v123, v123
	s_waitcnt lgkmcnt(3)
	v_mfma_f32_32x32x16_bf16 v[48:63], v[248:251], v[74:77], v[48:63]
	v_exp_f32_e32 v124, v124
	v_exp_f32_e32 v125, v125
	v_exp_f32_e32 v126, v126
	v_exp_f32_e32 v127, v127
	v_add_f32_e32 v244, v122, v124
	v_add_f32_e32 v245, v123, v125
	s_waitcnt lgkmcnt(2)
	v_mfma_f32_32x32x16_bf16 v[32:47], v[240:243], v[74:77], v[32:47]
	v_add_u32_e32 v254, s15, v213
	ds_read_b128 v[248:251], v254 offset:49152
	ds_read_b128 v[240:243], v254 offset:57344
	v_exp_f32_e32 v128, v128
	v_exp_f32_e32 v129, v129
	v_add_f32_e32 v244, v126, v244
	v_add_f32_e32 v245, v127, v245
	v_exp_f32_e32 v178, v178
	v_exp_f32_e32 v179, v179
	s_waitcnt lgkmcnt(3)
	v_mfma_f32_32x32x16_bf16 v[48:63], v[114:117], v[70:73], v[48:63]
	v_add_f32_e32 v244, v128, v244
	v_add_f32_e32 v245, v129, v245
	v_exp_f32_e32 v202, v202
	v_exp_f32_e32 v203, v203
	v_add_f32_e32 v244, v178, v244
	v_add_f32_e32 v245, v179, v245
	v_exp_f32_e32 v228, v228
	s_waitcnt vmcnt(0)
	v_add_u32_e32 v254, s22, v217
	v_add_u32_e32 v255, v254, v218
	v_add_u32_e32 v254, v254, v219
	ds_write_b128 v255, v[106:109]
	ds_write_b128 v254, v[110:113]
	s_cmp_eq_u64 s[2:3], 0
	s_cbranch_scc1 .Lattn_swA
	v_add_u32_e32 v254, s22, v186
	ds_write_b128 v254, v[102:105] offset:49152
.Lattn_swA:
	s_waitcnt lgkmcnt(4)
	v_mfma_f32_32x32x16_bf16 v[32:47], v[118:121], v[70:73], v[32:47]
	v_add_u32_e32 v254, s15, v214
	ds_read_b128 v[114:117], v254 offset:49152
	ds_read_b128 v[118:121], v254 offset:57344
	v_exp_f32_e32 v229, v229
	v_add_f32_e32 v244, v202, v244
	v_add_f32_e32 v245, v203, v245
	v_exp_f32_e32 v230, v230
	v_exp_f32_e32 v231, v231
	v_add_f32_e32 v244, v228, v244
	v_add_f32_e32 v245, v229, v245
	s_cmp_gt_u32 s17, 60
	s_cbranch_scc1 .Lattn_slA
	v_lshl_add_u64 v[90:91], s[40:41], 0, v[168:169]
	global_load_dwordx4 v[90:93], v[90:91], off
	v_lshl_add_u64 v[94:95], s[42:43], 0, v[168:169]
	global_load_dwordx4 v[94:97], v[94:95], off
	v_lshl_add_u64 v[98:99], s[26:27], 0, v[170:171]
	global_load_dwordx4 v[98:101], v[98:99], off
; #define SBAR() __builtin_amdgcn_sched_barrier(0)
; __device__ __forceinline__ void partialSM(f32x16& p0, f32x16& p1, float& m_reg, float& mn, float& alpha) {
;     constexpr float Cc = SCALE * 1.4426950408889634f;
;     float pmax = p0[0];
; #pragma unroll
;     for (int r = 1; r < 16; ++r) pmax = fmaxf(pmax, p0[r]);
; #pragma unroll
;     for (int r = 0; r < 16; ++r) pmax = fmaxf(pmax, p1[r]);
;     { auto rr = __builtin_amdgcn_permlane32_swap(__float_as_uint(pmax), __float_as_uint(pmax), false, false);
;       pmax = fmaxf(__uint_as_float(rr[0]), __uint_as_float(rr[1])); }
;     if (__builtin_expect(__all(pmax - m_reg <= THR / SCALE), 1)) { mn = m_reg; alpha = 1.f; }
;     else { mn = fmaxf(m_reg, pmax); alpha = __builtin_amdgcn_exp2f((m_reg - mn) * Cc); m_reg = mn; }
;     const float mnC = -mn * Cc;
;     { typedef float f32x2 __attribute__((ext_vector_type(2))); const f32x2 c2 = {Cc, Cc}, m2 = {mnC, mnC};
; #pragma unroll
;       for (int r = 0; r < 16; r += 2) { f32x2 t = {p0[r], p0[r + 1]}; t = __builtin_elementwise_fma(t, c2, m2); p0[r] = t.x; p0[r + 1] = t.y; }
; #pragma unroll
;       for (int r = 0; r < 16; r += 2) { f32x2 t = {p1[r], p1[r + 1]}; t = __builtin_elementwise_fma(t, c2, m2); p1[r] = t.x; p1[r + 1] = t.y; } }
; #pragma unroll
;     for (int r = 0; r < 16; ++r) p0[r] = __builtin_amdgcn_exp2f(p0[r]);
; }
; __device__ __forceinline__ void finishSM(f32x16& p0, f32x16& p1, float alpha, float& l_reg, bf16x8& pa0, bf16x8& pa1, bf16x8& pa2, bf16x8& pa3) {
; #pragma unroll
;     for (int r = 0; r < 16; ++r) p1[r] = __builtin_amdgcn_exp2f(p1[r]);
;     float ps;
;     { typedef float f32x2 __attribute__((ext_vector_type(2))); f32x2 s0 = {p0[0], p0[1]}, s1 = {p1[0], p1[1]};
; #pragma unroll
; __device__ __forceinline__ void attn_body(const bf16_t* __restrict__ Qb, const bf16_t* __restrict__ KVh, const bf16_t* __restrict__ KR, const float* __restrict__ ropeq,
;                                           bf16_t* __restrict__ Ob, int seq, char* lds, const int tid) {
;     ...
;         SBAR(); qkt(pA0, pA1, K_lds + bc * SHM_K, qr, r32, hi);
;         finishSM(pB0, pB1, alB, l_reg, pa0, pa1, pa2, pa3); SBAR();
;         if (j + 3 < NT) SLOAD(SE, (j + 3) * KVBLK); SBAR();
;         pv_d0(o, vb0 + bp * (int)SHM_V, pa0, pa1, pa2, pa3); partialSM(pA0, pA1, m_reg, mnA, alA);
;         SWAIT(); SWRITE(bn, SO);
;         RESC(alA); __syncthreads();
.Lattn_slA:
	s_waitcnt lgkmcnt(5)
	v_mfma_f32_32x32x16_bf16 v[48:63], v[248:251], v[66:69], v[48:63]
	v_add_f32_e32 v244, v230, v244
	v_add_f32_e32 v245, v231, v245
	v_add_f32_e32 v176, v244, v176
	v_add_f32_e32 v177, v245, v177
	v_cvt_pk_bf16_f32 v122, v122, v123
	v_cvt_pk_bf16_f32 v123, v124, v125
	v_cvt_pk_bf16_f32 v124, v126, v127
	s_waitcnt lgkmcnt(4)
	v_mfma_f32_32x32x16_bf16 v[32:47], v[240:243], v[66:69], v[32:47]
	v_add_u32_e32 v254, s15, v215
	ds_read_b128 v[248:251], v254 offset:49152
	ds_read_b128 v[240:243], v254 offset:57344
	v_cvt_pk_bf16_f32 v125, v128, v129
	v_cvt_pk_bf16_f32 v126, v178, v179
	v_cvt_pk_bf16_f32 v127, v202, v203
	v_cvt_pk_bf16_f32 v128, v228, v229
	v_cvt_pk_bf16_f32 v129, v230, v231
	s_waitcnt lgkmcnt(3)
	v_mfma_f32_32x32x16_bf16 v[48:63], v[114:117], v[82:85], v[48:63]
	v_add_f32_e32 v178, v176, v177
	v_add_f32_e32 v179, v177, v176
	v_mov_b32_e32 v228, v178
	s_nop 1
	v_permlane32_swap_b32_e32 v178, v228
	v_permlane32_swap_b32_e32 v122, v124
	s_waitcnt lgkmcnt(2)
	v_mfma_f32_32x32x16_bf16 v[32:47], v[118:121], v[82:85], v[32:47]
	v_add_u32_e32 v246, s14, v185
	ds_read_b64_tr_b16 v[114:115], v246 offset:0
	ds_read_b64_tr_b16 v[116:117], v246 offset:2048
	ds_read_b64_tr_b16 v[118:119], v246 offset:4096
	ds_read_b64_tr_b16 v[120:121], v246 offset:6144
	v_permlane32_swap_b32_e32 v123, v125
	v_permlane32_swap_b32_e32 v126, v128
	v_permlane32_swap_b32_e32 v127, v129
	s_waitcnt lgkmcnt(5)
	v_mfma_f32_32x32x16_bf16 v[48:63], v[248:251], v[86:89], v[48:63]
	s_waitcnt lgkmcnt(4)
	v_mfma_f32_32x32x16_bf16 v[32:47], v[240:243], v[86:89], v[32:47]
	ds_read_b64_tr_b16 v[248:249], v246 offset:8192
	ds_read_b64_tr_b16 v[250:251], v246 offset:10240
	ds_read_b64_tr_b16 v[240:241], v246 offset:12288
	ds_read_b64_tr_b16 v[242:243], v246 offset:14336
	s_waitcnt lgkmcnt(6)
	v_mfma_f32_32x32x16_bf16 v[0:15], v[232:235], v[114:117], v[0:15]
	ds_read_b64_tr_b16 v[114:115], v246 offset:512
	ds_read_b64_tr_b16 v[116:117], v246 offset:2560
	s_nop 1
	v_max_f32_e32 v244, v48, v49
	s_nop 0
	v_max_f32_e32 v245, v32, v33
	v_max3_f32 v244, v244, v50, v51
	v_max3_f32 v245, v245, v34, v35
	v_max3_f32 v244, v244, v52, v53
	v_max3_f32 v245, v245, v36, v37
	v_add_f32_e32 v247, v174, v175
	v_fmac_f32_e32 v247, v225, v163
	v_add_f32_e32 v163, v178, v228
	v_fmac_f32_e32 v163, v247, v227
	s_waitcnt lgkmcnt(6)
	v_mfma_f32_32x32x16_bf16 v[0:15], v[236:239], v[118:121], v[0:15]
	ds_read_b64_tr_b16 v[118:119], v246 offset:4608
	ds_read_b64_tr_b16 v[120:121], v246 offset:6656
	v_max3_f32 v244, v244, v54, v55
	v_max3_f32 v245, v245, v38, v39
	v_max3_f32 v244, v244, v56, v57
	v_max3_f32 v245, v245, v40, v41
	v_max3_f32 v244, v244, v58, v59
	v_max3_f32 v245, v245, v42, v43
	v_max3_f32 v244, v244, v60, v61
	s_waitcnt lgkmcnt(6)
	v_mfma_f32_32x32x16_bf16 v[0:15], v[122:125], v[248:251], v[0:15]
	ds_read_b64_tr_b16 v[248:249], v246 offset:8704
	ds_read_b64_tr_b16 v[250:251], v246 offset:10752
	v_max3_f32 v245, v245, v44, v45
	v_max3_f32 v244, v244, v62, v63
	v_max3_f32 v245, v245, v46, v47
	v_max_f32_e32 v244, v244, v245
	v_mov_b32_e32 v245, v244
	s_nop 1
	v_permlane32_swap_b32_e32 v244, v245
	v_max_f32_e32 v244, v244, v245
	v_sub_f32_e32 v247, v244, v180
	s_waitcnt lgkmcnt(6)
	v_mfma_f32_32x32x16_bf16 v[0:15], v[126:129], v[240:243], v[0:15]
	ds_read_b64_tr_b16 v[240:241], v246 offset:12800
	ds_read_b64_tr_b16 v[242:243], v246 offset:14848
	v_cmp_ge_f32_e32 vcc, s67, v247
	v_max_f32_e32 v244, v180, v244
	v_sub_f32_e32 v247, v180, v244
	v_mul_f32_e32 v247, 0x3e16c740, v247
	v_exp_f32_e32 v226, v247
	s_cmp_eq_u64 vcc, exec
	s_cselect_b64 s[44:45], -1, 0
	v_cndmask_b32_e64 v179, v244, v180, s[44:45]
	s_waitcnt lgkmcnt(6)
	v_mfma_f32_32x32x16_bf16 v[16:31], v[232:235], v[114:117], v[16:31]
	v_mul_f32_e32 v254, 0xbe16c740, v179
	v_cndmask_b32_e64 v226, v226, 1.0, s[44:45]
	v_fma_f32 v48, v48, s52, v254
	v_fma_f32 v49, v49, s52, v254
	v_fma_f32 v50, v50, s52, v254
	v_fma_f32 v51, v51, s52, v254
	v_fma_f32 v52, v52, s52, v254
	v_fma_f32 v53, v53, s52, v254
	v_fma_f32 v54, v54, s52, v254
	v_fma_f32 v55, v55, s52, v254
	v_fma_f32 v56, v56, s52, v254
	v_fma_f32 v57, v57, s52, v254
	v_fma_f32 v58, v58, s52, v254
	v_fma_f32 v59, v59, s52, v254
	v_exp_f32_e32 v116, v48
	v_exp_f32_e32 v117, v49
	v_exp_f32_e32 v114, v50
	v_exp_f32_e32 v115, v51
	s_waitcnt lgkmcnt(4)
	v_mfma_f32_32x32x16_bf16 v[16:31], v[236:239], v[118:121], v[16:31]
	v_fma_f32 v60, v60, s52, v254
	v_fma_f32 v61, v61, s52, v254
	v_fma_f32 v62, v62, s52, v254
	v_fma_f32 v63, v63, s52, v254
	v_fma_f32 v180, v32, s52, v254
	v_fma_f32 v181, v33, s52, v254
	v_fma_f32 v176, v34, s52, v254
	v_fma_f32 v177, v35, s52, v254
	v_exp_f32_e32 v112, v52
	v_exp_f32_e32 v113, v53
	v_exp_f32_e32 v110, v54
	v_exp_f32_e32 v111, v55
	v_fma_f32 v120, v44, s52, v254
	v_fma_f32 v121, v45, s52, v254
	v_fma_f32 v118, v46, s52, v254
	v_fma_f32 v119, v47, s52, v254
	s_waitcnt lgkmcnt(2)
	v_mfma_f32_32x32x16_bf16 v[16:31], v[122:125], v[248:251], v[16:31]
	v_exp_f32_e32 v108, v56
	v_exp_f32_e32 v109, v57
	v_exp_f32_e32 v106, v58
	v_exp_f32_e32 v107, v59
	v_exp_f32_e32 v102, v60
	v_exp_f32_e32 v103, v61
	v_exp_f32_e32 v104, v62
	v_exp_f32_e32 v105, v63
	v_fma_f32 v124, v40, s52, v254
	v_fma_f32 v125, v41, s52, v254
	v_fma_f32 v122, v42, s52, v254
	v_fma_f32 v123, v43, s52, v254
	s_waitcnt lgkmcnt(0)
	v_mfma_f32_32x32x16_bf16 v[16:31], v[126:129], v[240:243], v[16:31]
	v_fma_f32 v128, v36, s52, v254
	v_fma_f32 v129, v37, s52, v254
	v_fma_f32 v126, v38, s52, v254
	v_fma_f32 v127, v39, s52, v254
	v_cmp_gt_f32_e32 vcc, 1.0, v226
	s_cbranch_vccz .Lattn_rsA
	s_nop 7
	s_nop 5
	s_and_saveexec_b64 s[46:47], s[4:5]
	ds_write_b32 v216, v226 offset:128
	s_or_b64 exec, exec, s[46:47]
	s_waitcnt lgkmcnt(0)
	v_add_u32_e32 v232, v139, v187
	ds_read_b128 v[236:239], v232 offset:192
	ds_read_b128 v[240:243], v232 offset:160
	ds_read_b128 v[248:251], v232 offset:128
	ds_read_b128 v[232:235], v232 offset:224
	s_waitcnt lgkmcnt(0)
	v_mul_f32_e32 v12, v12, v232
	v_mul_f32_e32 v13, v13, v233
	v_mul_f32_e32 v14, v14, v234
	v_mul_f32_e32 v15, v15, v235
	v_mul_f32_e32 v8, v8, v236
	v_mul_f32_e32 v9, v9, v237
	v_mul_f32_e32 v10, v10, v238
	v_mul_f32_e32 v11, v11, v239
	v_mul_f32_e32 v4, v4, v240
	v_mul_f32_e32 v5, v5, v241
	v_mul_f32_e32 v6, v6, v242
	v_mul_f32_e32 v7, v7, v243
	v_mul_f32_e32 v0, v0, v248
	v_mul_f32_e32 v1, v1, v249
	v_mul_f32_e32 v2, v2, v250
	v_mul_f32_e32 v3, v3, v251
	v_mul_f32_e32 v28, v28, v232
	v_mul_f32_e32 v29, v29, v233
	v_mul_f32_e32 v30, v30, v234
	v_mul_f32_e32 v31, v31, v235
	v_mul_f32_e32 v24, v24, v236
	v_mul_f32_e32 v25, v25, v237
	v_mul_f32_e32 v26, v26, v238
	v_mul_f32_e32 v27, v27, v239
	v_mul_f32_e32 v20, v20, v240
	v_mul_f32_e32 v21, v21, v241
	v_mul_f32_e32 v22, v22, v242
	v_mul_f32_e32 v23, v23, v243
	v_mul_f32_e32 v16, v16, v248
	v_mul_f32_e32 v17, v17, v249
	v_mul_f32_e32 v18, v18, v250
	v_mul_f32_e32 v19, v19, v251
; #define SBAR() __builtin_amdgcn_sched_barrier(0)
; #define SLOAD(i, k0) do { sr_[i].a0 = *reinterpret_cast<const bf16x8*>(&KVh[(size_t)((k0) + sr) * NKV + c16 * 8]); sr_[i].a1 = *reinterpret_cast<const bf16x8*>(&KVh[(size_t)((k0) + 32 + sr) * NKV + c16 * 8]); \
;     sr_[i].rr = *reinterpret_cast<const bf16x8*>(&KR[(size_t)((k0) + rkey) * 32 + rch * 8]); } while (0)
; #define SWRITE(b, i) do { if (isK) { *(bf16x8*)(K_lds + (b) * SHM_K + kst0) = sr_[i].a0; *(bf16x8*)(K_lds + (b) * SHM_K + kst1) = sr_[i].a1; } \
;     else { *(bf16x8*)(V_lds + (b) * SHM_V + vst0) = sr_[i].a0; *(bf16x8*)(V_lds + (b) * SHM_V + vst1) = sr_[i].a1; } \
;     if (rwr) *(bf16x8*)(K_lds + (b) * SHM_K + rst) = sr_[i].rr; } while (0)
; #define SWAIT() asm volatile("s_waitcnt vmcnt(3)" ::: "memory")
; #define RESC(a) do { if (__any((a) < 1.f)) { if (hi == 0) al_l[r32] = (a); asm volatile("s_waitcnt lgkmcnt(0)" ::: "memory"); \
;     _Pragma("unroll") for (int d = 0; d < 2; ++d) _Pragma("unroll") for (int r = 0; r < 16; ++r) o[d][r] *= al_l[crow(r, hi)]; } } while (0)
; __device__ __forceinline__ void attn_body(const bf16_t* __restrict__ Qb, const bf16_t* __restrict__ KVh, const bf16_t* __restrict__ KR, const float* __restrict__ ropeq,
;                                           bf16_t* __restrict__ Ob, int seq, char* lds, const int tid) {
;     ...
;         if (j + 3 < NT) SLOAD(SE, (j + 3) * KVBLK); SBAR();
;         pv_d0(o, vb0 + bp * (int)SHM_V, pa0, pa1, pa2, pa3); partialSM(pA0, pA1, m_reg, mnA, alA);
;         SWAIT(); SWRITE(bn, SO);
;         RESC(alA); __syncthreads();
;         { const int t = bp; bp = bc; bc = bn; bn = t; }
;     }
.Lattn_rsA:
	s_cmp_gt_u32 s17, 60
	s_cselect_b64 s[12:13], -1, 0
	s_add_i32 s17, s17, 2
	v_lshl_add_u64 v[168:169], v[168:169], 0, s[56:57]
	v_lshl_add_u64 v[170:171], v[170:171], 0, s[24:25]
	v_lshl_add_u64 v[172:173], v[172:173], 0, s[24:25]
	s_and_b64 vcc, exec, s[12:13]
	s_waitcnt lgkmcnt(0)
	s_barrier
	s_cbranch_vccnz .LBB0_72
	s_mov_b32 s6, s18
	s_mov_b32 s18, s16
	s_mov_b32 s16, s19
	v_mov_b32_e32 v225, v226
	s_branch .Lattn_loop
